# PH2: CU partner blocks take n-adjacent tiles (shared A tile), remainder tiles one per CU
# baseline (speedup 1.0000x reference)
.LBB0_229:
	s_nop 0
	v_readlane_b32 s0, v208, 60
	v_readlane_b32 s1, v208, 61
	s_bitcmp1_b32 s0, 0
	v_readlane_b32 s0, v209, 60
	v_readlane_b32 s1, v209, 61
	s_cselect_b32 s60, 0xb80000, 0
	s_andn2_b64 vcc, exec, s[0:1]
	s_cbranch_vccnz .LBB0_617
	v_readlane_b32 s36, v210, 50
	s_lshl_b32 s0, s60, 1
	v_readlane_b32 s40, v210, 54
	v_readlane_b32 s41, v210, 55
	s_add_u32 s0, s40, s0
	s_addc_u32 s1, s41, 0
	s_lshl_b32 s6, s66, 7
	v_readlane_b32 s8, v209, 2
	s_lshr_b32 s7, s8, 8
	s_and_b32 s8, s8, 0xff
	s_lshl_b32 s8, s8, 1
	s_or_b32 s8, s8, s7
	s_lshl_b32 s7, s8, 7
	v_readlane_b32 s37, v210, 51
	v_readlane_b32 s38, v210, 52
	v_readlane_b32 s39, v210, 53
	v_readlane_b32 s42, v210, 56
	v_readlane_b32 s43, v210, 57
	v_readlane_b32 s44, v210, 58
	v_readlane_b32 s45, v210, 59
	v_readlane_b32 s46, v210, 60
	v_readlane_b32 s47, v210, 61
	v_readlane_b32 s48, v210, 62
	v_readlane_b32 s49, v210, 63
	v_readlane_b32 s50, v209, 0
	v_readlane_b32 s51, v209, 1
	s_branch .LBB0_232
.LBB0_231:
	s_or_b64 exec, exec, s[2:3]
	s_add_i32 s8, s8, s66
	s_add_i32 s7, s7, s6
	s_cmpk_lt_i32 s8, 0xa00
	s_cbranch_scc1 .LBB0_232
	s_cmpk_ge_i32 s8, 0xc00
	s_cbranch_scc1 .LBB0_616
	v_readlane_b32 s8, v209, 2
	s_addk_i32 s8, 0xa00
	s_lshl_b32 s7, s8, 7
	s_cmpk_lt_i32 s8, 0xaa0
	s_cbranch_scc0 .LBB0_616
